# attention: map-1 waves touch the next unit's first K/V tile and Q rows (one dword per 128-byte line, result discarded) before the epilogue so the next prologue's loads hit L2
# baseline (speedup 1.0000x reference)
; __device__ __forceinline__ void phase_attn(const PT& p, LAS unsigned char* lds, int tid, int lane, int wave) {
;     ...
;     for (int u = blockIdx.x; u < NBATCH * 16 * 8; u += gridDim.x) {
;         const int j = u & 7, hd = (u >> 3) & 15, b = u >> 7;
; #pragma unroll 1
;         for (int k = 0; k < 2; ++k) attn_unit(p, lds, tid, lane, wave, b, hd, k == 0 ? 15 - j : j, lam);
.LBB0_1106:
	s_andn2_b64 vcc, exec, s[60:61]
	s_cbranch_vccnz .Lfin_nopf
	v_or_b32_e32 v8, s91, v241
	v_and_b32_e32 v9, 31, v198
	v_lshlrev_b32_e32 v9, 11, v9
	v_sub_u32_e32 v8, v8, v9
	v_lshrrev_b32_e32 v10, 4, v198
	v_lshl_add_u32 v8, v10, 11, v8
	v_and_b32_e32 v11, 15, v198
	v_lshl_add_u32 v8, v11, 3, v8
	v_lshlrev_b32_e32 v14, 1, v8
	s_mov_b64 s[98:99], s[2:3]
	global_load_dwordx4 v[134:137], v14, s[98:99]
	s_add_u32 s98, s98, 0x4000
	s_addc_u32 s99, s99, 0
	global_load_dwordx4 v[138:141], v14, s[98:99]
	s_add_u32 s98, s98, 0x4000
	s_addc_u32 s99, s99, 0
	global_load_dwordx4 v[154:157], v14, s[98:99]
	s_add_u32 s98, s98, 0x4000
	s_addc_u32 s99, s99, 0
	global_load_dwordx4 v[158:161], v14, s[98:99]
	s_add_u32 s98, s98, 0x4000
	s_addc_u32 s99, s99, 0
	global_load_dwordx4 v[162:165], v14, s[98:99]
	s_add_u32 s98, s98, 0x4000
	s_addc_u32 s99, s99, 0
	global_load_dwordx4 v[166:169], v14, s[98:99]
	s_add_u32 s98, s98, 0x4000
	s_addc_u32 s99, s99, 0
	global_load_dwordx4 v[170:173], v14, s[98:99]
	s_add_u32 s98, s98, 0x4000
	s_addc_u32 s99, s99, 0
	global_load_dwordx4 v[174:177], v14, s[98:99]
	s_and_b64 vcc, exec, s[76:77]
	s_cbranch_vccnz .Lnup_u
	s_mov_b32 s100, s94
	s_mov_b32 s101, s91
	s_mov_b32 s99, s92
	s_branch .Lnup_go
.Lnup_u:
	v_readlane_b32 s36, v249, 0
	s_nop 3
	s_add_i32 s36, s90, s36
	s_cmpk_gt_i32 s36, 0x3ff
	s_cbranch_scc1 .Lnup_none
	s_and_b32 s98, s36, 0xffffffc0
	s_bfe_u32 s99, s36, 0x30003
	s_or_b32 s98, s98, s99
	s_and_b32 s99, s36, 7
	s_lshl_b32 s99, s99, 3
	s_or_b32 s98, s98, s99
	s_lshr_b32 s99, s36, 8
	s_and_b32 s37, s99, 1
	s_mul_i32 s37, s37, 7
	s_lshr_b32 s99, s99, 1
	s_lshl_b32 s99, s99, 3
	s_or_b32 s99, s99, s37
	s_bfe_u32 s37, s98, 0x40003
	s_xor_b32 s37, s37, s99
	s_lshl_b32 s101, s37, 7
	s_lshl_b32 s100, s98, 4
	s_and_b32 s100, s100, 0xfffff800
	s_mov_b32 s99, s93
.Lnup_go:
	s_lshl_b32 s99, s99, 7
	s_add_i32 s100, s100, s99
	v_and_b32_e32 v8, 0xff, v196
	v_lshrrev_b32_e32 v9, 1, v8
	v_and_b32_e32 v10, 1, v8
	v_add_u32_e32 v9, s100, v9
	v_lshl_add_u32 v9, v9, 11, s101
	v_lshlrev_b32_e32 v9, 1, v9
	v_lshl_add_u32 v9, v10, 7, v9
	global_load_dword v17, v9, s[46:47]
	global_load_dword v17, v9, s[42:43]
	v_bfe_u32 v11, v196, 6, 2
	v_and_b32_e32 v12, 31, v198
	v_lshl_or_b32 v11, v11, 5, v12
	v_lshrrev_b32_e32 v12, 5, v198
	v_add_u32_e32 v11, s100, v11
	v_lshl_add_u32 v11, v11, 11, s101
	v_lshlrev_b32_e32 v11, 1, v11
	v_lshl_add_u32 v11, v12, 7, v11
	global_load_dword v17, v11, s[40:41]
	s_branch .Lfin_nopf
.Lnup_none:
	global_load_dword v17, v14, s[2:3]
	global_load_dword v17, v14, s[2:3]
	global_load_dword v17, v14, s[2:3]

; __device__ __forceinline__ void attn_unit(const PT& p, LAS unsigned char* lds, int tid, int lane, int wave, int b, int hd, int qb, float lam) {
;     ...
;         const float i1 = 1.f / lt; float ss = 0.f;
; #pragma unroll
;         for (int db = 0; db < 4; ++db)
; #pragma unroll
;             for (int i = 0; i < 16; ++i) { const float o = oT[db][i] * i1 - xch[(db * 16 + i) * 64 + lane]; oT[db][i] = o; ss += o * o; }
;         ss += __shfl_xor(ss, 32);
;         const float rn = rsqrtf(ss * (1.f / 128.f) + EPS) * (1.f - LAMBDA_INIT);
;     ...
;                 const int d = db * 32 + 8 * qd + 4 * h; const unsigned off = tokq * 2048u + (unsigned)(hd * 128 + d);
;                 const u32x2 gg = *(const u32x2*)(Gb + off); const f32x4 sg = *(const f32x4*)(p.in[20] + d);
.LBB0_1108:
	s_andn2_b64 vcc, exec, s[60:61]
	s_waitcnt lgkmcnt(0)
	s_barrier
	s_cbranch_vccnz .LBB0_1073
	v_div_scale_f32 v5, s[36:37], v4, v4, 1.0
	v_rcp_f32_e32 v6, v5
	v_div_scale_f32 v7, vcc, 1.0, v4, 1.0
	ds_read_b64 v[2:3], v233
	v_fma_f32 v130, -v5, v6, 1.0
	v_fmac_f32_e32 v6, v130, v6
	v_mul_f32_e32 v132, v7, v6
	v_fma_f32 v133, -v5, v132, v7
	v_fmac_f32_e32 v132, v133, v6
	v_fma_f32 v5, -v5, v132, v7
	v_div_fmas_f32 v5, v5, v6, v132
	v_div_fixup_f32 v5, v5, v4, 1.0
	ds_read2st64_b32 v[52:53], v0 offset1:1
	ds_read2st64_b32 v[54:55], v0 offset0:2 offset1:3
	ds_read2st64_b32 v[56:57], v0 offset0:4 offset1:5
	ds_read2st64_b32 v[58:59], v0 offset0:6 offset1:7
	ds_read2st64_b32 v[60:61], v0 offset0:8 offset1:9
	ds_read2st64_b32 v[62:63], v0 offset0:10 offset1:11
	ds_read2st64_b32 v[64:65], v0 offset0:12 offset1:13
	ds_read2st64_b32 v[142:143], v0 offset0:14 offset1:15
	ds_read2st64_b32 v[144:145], v0 offset0:16 offset1:17
	ds_read2st64_b32 v[146:147], v0 offset0:18 offset1:19
	ds_read2st64_b32 v[148:149], v0 offset0:20 offset1:21
	ds_read2st64_b32 v[150:151], v0 offset0:22 offset1:23
	ds_read2st64_b32 v[152:153], v0 offset0:24 offset1:25
	ds_read2st64_b32 v[8:9], v0 offset0:26 offset1:27
	ds_read2st64_b32 v[10:11], v0 offset0:28 offset1:29
	ds_read2st64_b32 v[12:13], v0 offset0:30 offset1:31
	s_bitcmp1_b32 s95, 0
	s_cselect_b32 s38, 0x11000, 0
	v_bfe_u32 v6, v196, 6, 2
	v_mul_u32_u24_e32 v6, 0x2200, v6
	v_add_u32_e32 v6, s38, v6
	v_lshrrev_b32_e32 v7, 4, v198
	v_mul_u32_u24_e32 v7, 0x110, v7
	v_and_b32_e32 v130, 15, v198
	v_lshl_add_u32 v15, v130, 4, v7
	v_add_u32_e32 v15, v15, v6
	v_and_b32_e32 v7, 31, v198
	v_mul_u32_u24_e32 v7, 0x110, v7
	v_lshl_add_u32 v7, v178, 1, v7
	v_add_u32_e32 v1, v7, v6
	s_waitcnt lgkmcnt(0)
	v_readfirstlane_b32 s36, v2
	v_readfirstlane_b32 s37, v3
	v_lshlrev_b32_e32 v130, 2, v178
	s_nop 4
	global_load_dwordx4 v[18:21], v130, s[36:37]
	global_load_dwordx4 v[22:25], v130, s[36:37] offset:32
	global_load_dwordx4 v[26:29], v130, s[36:37] offset:64
	global_load_dwordx4 v[30:33], v130, s[36:37] offset:96
	global_load_dwordx4 v[34:37], v130, s[36:37] offset:128
	global_load_dwordx4 v[38:41], v130, s[36:37] offset:160
	global_load_dwordx4 v[42:45], v130, s[36:37] offset:192
	global_load_dwordx4 v[46:49], v130, s[36:37] offset:224
	v_fma_f32 v114, v114, v5, -v52
	v_fma_f32 v115, v115, v5, -v53
	v_mul_f32_e32 v6, v114, v114
	v_mul_f32_e32 v7, v115, v115
	v_fma_f32 v116, v116, v5, -v54
	v_fma_f32 v117, v117, v5, -v55
	v_fmac_f32_e32 v6, v116, v116
	v_fmac_f32_e32 v7, v117, v117
	v_fma_f32 v118, v118, v5, -v56
	v_fma_f32 v119, v119, v5, -v57
	v_fmac_f32_e32 v6, v118, v118
	v_fmac_f32_e32 v7, v119, v119
	v_fma_f32 v120, v120, v5, -v58
	v_fma_f32 v121, v121, v5, -v59
	v_fmac_f32_e32 v6, v120, v120
	v_fmac_f32_e32 v7, v121, v121
	v_fma_f32 v122, v122, v5, -v60
	v_fma_f32 v123, v123, v5, -v61
	v_fmac_f32_e32 v6, v122, v122
	v_fmac_f32_e32 v7, v123, v123
	v_fma_f32 v124, v124, v5, -v62
	v_fma_f32 v125, v125, v5, -v63
	v_fmac_f32_e32 v6, v124, v124
	v_fmac_f32_e32 v7, v125, v125
	v_fma_f32 v126, v126, v5, -v64
	v_fma_f32 v127, v127, v5, -v65
	v_fmac_f32_e32 v6, v126, v126
	v_fmac_f32_e32 v7, v127, v127
	v_fma_f32 v128, v128, v5, -v142
	v_fma_f32 v129, v129, v5, -v143
	v_fmac_f32_e32 v6, v128, v128
	v_fmac_f32_e32 v7, v129, v129
	v_fma_f32 v98, v98, v5, -v144
	v_fma_f32 v99, v99, v5, -v145
	v_fmac_f32_e32 v6, v98, v98
	v_fmac_f32_e32 v7, v99, v99
	v_fma_f32 v100, v100, v5, -v146
	v_fma_f32 v101, v101, v5, -v147
	v_fmac_f32_e32 v6, v100, v100
	v_fmac_f32_e32 v7, v101, v101
	v_fma_f32 v102, v102, v5, -v148
	v_fma_f32 v103, v103, v5, -v149
	v_fmac_f32_e32 v6, v102, v102
	v_fmac_f32_e32 v7, v103, v103
	v_fma_f32 v104, v104, v5, -v150
	v_fma_f32 v105, v105, v5, -v151
	v_fmac_f32_e32 v6, v104, v104
	v_fmac_f32_e32 v7, v105, v105
	v_fma_f32 v106, v106, v5, -v152
	v_fma_f32 v107, v107, v5, -v153
	v_fmac_f32_e32 v6, v106, v106
	v_fmac_f32_e32 v7, v107, v107
	v_fma_f32 v108, v108, v5, -v8
	v_fma_f32 v109, v109, v5, -v9
	v_fmac_f32_e32 v6, v108, v108
	v_fmac_f32_e32 v7, v109, v109
	v_fma_f32 v110, v110, v5, -v10
	v_fma_f32 v111, v111, v5, -v11
	v_fmac_f32_e32 v6, v110, v110
	v_fmac_f32_e32 v7, v111, v111
	v_fma_f32 v112, v112, v5, -v12
	v_fma_f32 v113, v113, v5, -v13
	v_fmac_f32_e32 v6, v112, v112
	v_fmac_f32_e32 v7, v113, v113
	ds_read2st64_b32 v[52:53], v0 offset0:32 offset1:33
	ds_read2st64_b32 v[54:55], v0 offset0:34 offset1:35
	ds_read2st64_b32 v[56:57], v0 offset0:36 offset1:37
	ds_read2st64_b32 v[58:59], v0 offset0:38 offset1:39
	ds_read2st64_b32 v[60:61], v0 offset0:40 offset1:41
	ds_read2st64_b32 v[62:63], v0 offset0:42 offset1:43
	ds_read2st64_b32 v[64:65], v0 offset0:44 offset1:45
	ds_read2st64_b32 v[142:143], v0 offset0:46 offset1:47
	ds_read2st64_b32 v[144:145], v0 offset0:48 offset1:49
	ds_read2st64_b32 v[146:147], v0 offset0:50 offset1:51
	ds_read2st64_b32 v[148:149], v0 offset0:52 offset1:53
	ds_read2st64_b32 v[150:151], v0 offset0:54 offset1:55
	ds_read2st64_b32 v[152:153], v0 offset0:56 offset1:57
	ds_read2st64_b32 v[8:9], v0 offset0:58 offset1:59
	ds_read2st64_b32 v[10:11], v0 offset0:60 offset1:61
	ds_read2st64_b32 v[12:13], v0 offset0:62 offset1:63
	s_waitcnt vmcnt(18)
	ds_write_b128 v15, v[134:137]
	s_waitcnt vmcnt(17)
	ds_write_b128 v15, v[138:141] offset:1088
	s_waitcnt vmcnt(16)
	ds_write_b128 v15, v[154:157] offset:2176
	s_waitcnt vmcnt(15)
	ds_write_b128 v15, v[158:161] offset:3264
	s_waitcnt vmcnt(14)
	ds_write_b128 v15, v[162:165] offset:4352
	s_waitcnt vmcnt(13)
	ds_write_b128 v15, v[166:169] offset:5440
	s_waitcnt vmcnt(12)
	ds_write_b128 v15, v[170:173] offset:6528
	s_waitcnt vmcnt(11)
; __device__ __forceinline__ float bflo(unsigned u) { return __uint_as_float(u << 16); }
; __device__ __forceinline__ float bfhi(unsigned u) { return __uint_as_float(u & 0xffff0000u); }
; __device__ __forceinline__ void attn_unit(const PT& p, LAS unsigned char* lds, int tid, int lane, int wave, int b, int hd, int qb, float lam) {
;     ...
;             for (int i = 0; i < 16; ++i) { const float o = oT[db][i] * i1 - xch[(db * 16 + i) * 64 + lane]; oT[db][i] = o; ss += o * o; }
;         ss += __shfl_xor(ss, 32);
;         const float rn = rsqrtf(ss * (1.f / 128.f) + EPS) * (1.f - LAMBDA_INIT);
; #pragma unroll
;         for (int db = 0; db < 4; ++db)
; #pragma unroll
;             for (int qd = 0; qd < 4; ++qd) {
;                 const int d = db * 32 + 8 * qd + 4 * h; const unsigned off = tokq * 2048u + (unsigned)(hd * 128 + d);
;                 const u32x2 gg = *(const u32x2*)(Gb + off); const f32x4 sg = *(const f32x4*)(p.in[20] + d);
;                 u32x2 w; w.x = pk2(oT[db][4 * qd] * rn * sg.x * bflo(gg.x), oT[db][4 * qd + 1] * rn * sg.y * bfhi(gg.x));
;                 w.y = pk2(oT[db][4 * qd + 2] * rn * sg.z * bflo(gg.y), oT[db][4 * qd + 3] * rn * sg.w * bfhi(gg.y));
;                 *(u32x2*)(Ob + off) = w;
	ds_write_b128 v15, v[174:177] offset:7616
	global_load_dwordx4 v[134:137], v130, s[36:37] offset:256
	global_load_dwordx4 v[138:141], v130, s[36:37] offset:288
	global_load_dwordx4 v[154:157], v130, s[36:37] offset:320
	global_load_dwordx4 v[158:161], v130, s[36:37] offset:352
	global_load_dwordx4 v[162:165], v130, s[36:37] offset:384
	global_load_dwordx4 v[166:169], v130, s[36:37] offset:416
	global_load_dwordx4 v[170:173], v130, s[36:37] offset:448
	global_load_dwordx4 v[174:177], v130, s[36:37] offset:480
	s_waitcnt lgkmcnt(8)
	v_fma_f32 v82, v82, v5, -v52
	v_fma_f32 v83, v83, v5, -v53
	v_fmac_f32_e32 v6, v82, v82
	v_fmac_f32_e32 v7, v83, v83
	v_fma_f32 v84, v84, v5, -v54
	v_fma_f32 v85, v85, v5, -v55
	v_fmac_f32_e32 v6, v84, v84
	v_fmac_f32_e32 v7, v85, v85
	v_fma_f32 v86, v86, v5, -v56
	v_fma_f32 v87, v87, v5, -v57
	v_fmac_f32_e32 v6, v86, v86
	v_fmac_f32_e32 v7, v87, v87
	v_fma_f32 v88, v88, v5, -v58
	v_fma_f32 v89, v89, v5, -v59
	v_fmac_f32_e32 v6, v88, v88
	v_fmac_f32_e32 v7, v89, v89
	v_fma_f32 v90, v90, v5, -v60
	v_fma_f32 v91, v91, v5, -v61
	v_fmac_f32_e32 v6, v90, v90
	v_fmac_f32_e32 v7, v91, v91
	v_fma_f32 v92, v92, v5, -v62
	v_fma_f32 v93, v93, v5, -v63
	v_fmac_f32_e32 v6, v92, v92
	v_fmac_f32_e32 v7, v93, v93
	v_fma_f32 v94, v94, v5, -v64
	v_fma_f32 v95, v95, v5, -v65
	v_fmac_f32_e32 v6, v94, v94
	v_fmac_f32_e32 v7, v95, v95
	v_fma_f32 v96, v96, v5, -v142
	v_fma_f32 v97, v97, v5, -v143
	v_fmac_f32_e32 v6, v96, v96
	v_fmac_f32_e32 v7, v97, v97
	v_fma_f32 v66, v66, v5, -v144
	v_fma_f32 v67, v67, v5, -v145
	v_fmac_f32_e32 v6, v66, v66
	v_fmac_f32_e32 v7, v67, v67
	v_fma_f32 v68, v68, v5, -v146
	v_fma_f32 v69, v69, v5, -v147
	v_fmac_f32_e32 v6, v68, v68
	v_fmac_f32_e32 v7, v69, v69
	v_fma_f32 v70, v70, v5, -v148
	v_fma_f32 v71, v71, v5, -v149
	v_fmac_f32_e32 v6, v70, v70
	v_fmac_f32_e32 v7, v71, v71
	v_fma_f32 v72, v72, v5, -v150
	v_fma_f32 v73, v73, v5, -v151
	v_fmac_f32_e32 v6, v72, v72
	v_fmac_f32_e32 v7, v73, v73
	v_fma_f32 v74, v74, v5, -v152
	v_fma_f32 v75, v75, v5, -v153
	v_fmac_f32_e32 v6, v74, v74
	v_fmac_f32_e32 v7, v75, v75
	v_fma_f32 v76, v76, v5, -v8
	v_fma_f32 v77, v77, v5, -v9
	v_fmac_f32_e32 v6, v76, v76
	v_fmac_f32_e32 v7, v77, v77
	v_fma_f32 v78, v78, v5, -v10
	v_fma_f32 v79, v79, v5, -v11
	v_fmac_f32_e32 v6, v78, v78
	v_fmac_f32_e32 v7, v79, v79
	v_fma_f32 v80, v80, v5, -v12
	v_fma_f32 v81, v81, v5, -v13
	v_fmac_f32_e32 v6, v80, v80
	v_fmac_f32_e32 v7, v81, v81
	v_add_f32_e32 v6, v6, v7
	ds_bpermute_b32 v7, v197, v6
	s_mov_b32 s38, 0x800000
	s_waitcnt lgkmcnt(0)
	v_add_f32_e32 v6, v6, v7
	v_fmamk_f32 v6, v6, 0x3c000000, v234
	v_mul_f32_e32 v7, 0x4b800000, v6
	v_cmp_gt_f32_e32 vcc, s38, v6
	s_nop 1
	v_cndmask_b32_e32 v6, v6, v7, vcc
	v_rsq_f32_e32 v7, v6
	s_nop 0
	v_mul_f32_e32 v6, 0x45800000, v7
	v_cndmask_b32_e32 v6, v7, v6, vcc
	v_mul_f32_e32 v50, 0x3f24fd5c, v6
	ds_read_b64 v[52:53], v1
	ds_read_b64 v[54:55], v1 offset:16
	s_waitcnt vmcnt(15)
	v_mul_f32_e32 v56, v114, v50
	v_mul_f32_e32 v57, v115, v50
	v_mul_f32_e32 v58, v116, v50
	v_mul_f32_e32 v59, v117, v50
	v_mul_f32_e32 v56, v18, v56
	v_mul_f32_e32 v57, v19, v57
	v_mul_f32_e32 v58, v20, v58
	v_mul_f32_e32 v59, v21, v59
	s_waitcnt lgkmcnt(1)
	v_lshlrev_b32_e32 v60, 16, v52
	v_and_b32_e32 v61, 0xffff0000, v52
	v_lshlrev_b32_e32 v62, 16, v53
	v_and_b32_e32 v63, 0xffff0000, v53
	v_mul_f32_e32 v56, v56, v60
	v_mul_f32_e32 v57, v57, v61
	v_mul_f32_e32 v58, v58, v62
	v_mul_f32_e32 v59, v59, v63
	v_cvt_pk_bf16_f32 v52, v56, v57
	v_cvt_pk_bf16_f32 v53, v58, v59
	ds_write_b64 v1, v[52:53]
	ds_read_b64 v[52:53], v1 offset:32
	s_waitcnt vmcnt(14)
	v_mul_f32_e32 v56, v118, v50
	v_mul_f32_e32 v57, v119, v50
	v_mul_f32_e32 v58, v120, v50
	v_mul_f32_e32 v59, v121, v50
	v_mul_f32_e32 v56, v22, v56
	v_mul_f32_e32 v57, v23, v57
	v_mul_f32_e32 v58, v24, v58
	v_mul_f32_e32 v59, v25, v59
	s_waitcnt lgkmcnt(1)
	v_lshlrev_b32_e32 v60, 16, v54
	v_and_b32_e32 v61, 0xffff0000, v54
	v_lshlrev_b32_e32 v62, 16, v55
	v_and_b32_e32 v63, 0xffff0000, v55
	v_mul_f32_e32 v56, v56, v60
	v_mul_f32_e32 v57, v57, v61
	v_mul_f32_e32 v58, v58, v62
	v_mul_f32_e32 v59, v59, v63
	v_cvt_pk_bf16_f32 v54, v56, v57
	v_cvt_pk_bf16_f32 v55, v58, v59
	ds_write_b64 v1, v[54:55] offset:16
	ds_read_b64 v[54:55], v1 offset:48
	s_waitcnt vmcnt(13)
	v_mul_f32_e32 v56, v122, v50
	v_mul_f32_e32 v57, v123, v50
	v_mul_f32_e32 v58, v124, v50
	v_mul_f32_e32 v59, v125, v50
	v_mul_f32_e32 v56, v26, v56
	v_mul_f32_e32 v57, v27, v57
	v_mul_f32_e32 v58, v28, v58
	v_mul_f32_e32 v59, v29, v59
	s_waitcnt lgkmcnt(1)
	v_lshlrev_b32_e32 v60, 16, v52
	v_and_b32_e32 v61, 0xffff0000, v52
	v_lshlrev_b32_e32 v62, 16, v53
	v_and_b32_e32 v63, 0xffff0000, v53
	v_mul_f32_e32 v56, v56, v60
	v_mul_f32_e32 v57, v57, v61
	v_mul_f32_e32 v58, v58, v62
	v_mul_f32_e32 v59, v59, v63
	v_cvt_pk_bf16_f32 v52, v56, v57
	v_cvt_pk_bf16_f32 v53, v58, v59
	ds_write_b64 v1, v[52:53] offset:32
	ds_read_b64 v[52:53], v1 offset:64
	s_waitcnt vmcnt(12)
	v_mul_f32_e32 v56, v126, v50
	v_mul_f32_e32 v57, v127, v50
	v_mul_f32_e32 v58, v128, v50
	v_mul_f32_e32 v59, v129, v50
	v_mul_f32_e32 v56, v30, v56
	v_mul_f32_e32 v57, v31, v57
	v_mul_f32_e32 v58, v32, v58
	v_mul_f32_e32 v59, v33, v59
	s_waitcnt lgkmcnt(1)
	v_lshlrev_b32_e32 v60, 16, v54
	v_and_b32_e32 v61, 0xffff0000, v54
	v_lshlrev_b32_e32 v62, 16, v55
	v_and_b32_e32 v63, 0xffff0000, v55
	v_mul_f32_e32 v56, v56, v60
	v_mul_f32_e32 v57, v57, v61
	v_mul_f32_e32 v58, v58, v62
	v_mul_f32_e32 v59, v59, v63
	v_cvt_pk_bf16_f32 v54, v56, v57
	v_cvt_pk_bf16_f32 v55, v58, v59
	ds_write_b64 v1, v[54:55] offset:48
	ds_read_b64 v[54:55], v1 offset:80
	s_waitcnt vmcnt(11)
; __device__ __forceinline__ float bflo(unsigned u) { return __uint_as_float(u << 16); }
; __device__ __forceinline__ float bfhi(unsigned u) { return __uint_as_float(u & 0xffff0000u); }
; __device__ __forceinline__ void attn_unit(const PT& p, LAS unsigned char* lds, int tid, int lane, int wave, int b, int hd, int qb, float lam) {
;     ...
;         for (int db = 0; db < 4; ++db)
; #pragma unroll
;             for (int qd = 0; qd < 4; ++qd) {
;                 const int d = db * 32 + 8 * qd + 4 * h; const unsigned off = tokq * 2048u + (unsigned)(hd * 128 + d);
;                 const u32x2 gg = *(const u32x2*)(Gb + off); const f32x4 sg = *(const f32x4*)(p.in[20] + d);
;                 u32x2 w; w.x = pk2(oT[db][4 * qd] * rn * sg.x * bflo(gg.x), oT[db][4 * qd + 1] * rn * sg.y * bfhi(gg.x));
;                 w.y = pk2(oT[db][4 * qd + 2] * rn * sg.z * bflo(gg.y), oT[db][4 * qd + 3] * rn * sg.w * bfhi(gg.y));
;                 *(u32x2*)(Ob + off) = w;
	v_mul_f32_e32 v56, v98, v50
	v_mul_f32_e32 v57, v99, v50
	v_mul_f32_e32 v58, v100, v50
	v_mul_f32_e32 v59, v101, v50
	v_mul_f32_e32 v56, v34, v56
	v_mul_f32_e32 v57, v35, v57
	v_mul_f32_e32 v58, v36, v58
	v_mul_f32_e32 v59, v37, v59
	s_waitcnt lgkmcnt(1)
	v_lshlrev_b32_e32 v60, 16, v52
	v_and_b32_e32 v61, 0xffff0000, v52
	v_lshlrev_b32_e32 v62, 16, v53
	v_and_b32_e32 v63, 0xffff0000, v53
	v_mul_f32_e32 v56, v56, v60
	v_mul_f32_e32 v57, v57, v61
	v_mul_f32_e32 v58, v58, v62
	v_mul_f32_e32 v59, v59, v63
	v_cvt_pk_bf16_f32 v52, v56, v57
	v_cvt_pk_bf16_f32 v53, v58, v59
	ds_write_b64 v1, v[52:53] offset:64
	ds_read_b64 v[52:53], v1 offset:96
	s_waitcnt vmcnt(10)
	v_mul_f32_e32 v56, v102, v50
	v_mul_f32_e32 v57, v103, v50
	v_mul_f32_e32 v58, v104, v50
	v_mul_f32_e32 v59, v105, v50
	v_mul_f32_e32 v56, v38, v56
	v_mul_f32_e32 v57, v39, v57
	v_mul_f32_e32 v58, v40, v58
	v_mul_f32_e32 v59, v41, v59
	s_waitcnt lgkmcnt(1)
	v_lshlrev_b32_e32 v60, 16, v54
	v_and_b32_e32 v61, 0xffff0000, v54
	v_lshlrev_b32_e32 v62, 16, v55
	v_and_b32_e32 v63, 0xffff0000, v55
	v_mul_f32_e32 v56, v56, v60
	v_mul_f32_e32 v57, v57, v61
	v_mul_f32_e32 v58, v58, v62
	v_mul_f32_e32 v59, v59, v63
	v_cvt_pk_bf16_f32 v54, v56, v57
	v_cvt_pk_bf16_f32 v55, v58, v59
	ds_write_b64 v1, v[54:55] offset:80
	ds_read_b64 v[54:55], v1 offset:112
	s_waitcnt vmcnt(9)
	v_mul_f32_e32 v56, v106, v50
	v_mul_f32_e32 v57, v107, v50
	v_mul_f32_e32 v58, v108, v50
	v_mul_f32_e32 v59, v109, v50
	v_mul_f32_e32 v56, v42, v56
	v_mul_f32_e32 v57, v43, v57
	v_mul_f32_e32 v58, v44, v58
	v_mul_f32_e32 v59, v45, v59
	s_waitcnt lgkmcnt(1)
	v_lshlrev_b32_e32 v60, 16, v52
	v_and_b32_e32 v61, 0xffff0000, v52
	v_lshlrev_b32_e32 v62, 16, v53
	v_and_b32_e32 v63, 0xffff0000, v53
	v_mul_f32_e32 v56, v56, v60
	v_mul_f32_e32 v57, v57, v61
	v_mul_f32_e32 v58, v58, v62
	v_mul_f32_e32 v59, v59, v63
	v_cvt_pk_bf16_f32 v52, v56, v57
	v_cvt_pk_bf16_f32 v53, v58, v59
	ds_write_b64 v1, v[52:53] offset:96
	ds_read_b64 v[52:53], v1 offset:128
	s_waitcnt vmcnt(8)
	v_mul_f32_e32 v56, v110, v50
	v_mul_f32_e32 v57, v111, v50
	v_mul_f32_e32 v58, v112, v50
	v_mul_f32_e32 v59, v113, v50
	v_mul_f32_e32 v56, v46, v56
	v_mul_f32_e32 v57, v47, v57
	v_mul_f32_e32 v58, v48, v58
	v_mul_f32_e32 v59, v49, v59
	s_waitcnt lgkmcnt(1)
	v_lshlrev_b32_e32 v60, 16, v54
	v_and_b32_e32 v61, 0xffff0000, v54
	v_lshlrev_b32_e32 v62, 16, v55
	v_and_b32_e32 v63, 0xffff0000, v55
	v_mul_f32_e32 v56, v56, v60
	v_mul_f32_e32 v57, v57, v61
	v_mul_f32_e32 v58, v58, v62
	v_mul_f32_e32 v59, v59, v63
	v_cvt_pk_bf16_f32 v54, v56, v57
	v_cvt_pk_bf16_f32 v55, v58, v59
	ds_write_b64 v1, v[54:55] offset:112
	ds_read_b64 v[54:55], v1 offset:144
	s_waitcnt vmcnt(7)
	v_mul_f32_e32 v56, v82, v50
	v_mul_f32_e32 v57, v83, v50
	v_mul_f32_e32 v58, v84, v50
	v_mul_f32_e32 v59, v85, v50
	v_mul_f32_e32 v56, v134, v56
	v_mul_f32_e32 v57, v135, v57
	v_mul_f32_e32 v58, v136, v58
	v_mul_f32_e32 v59, v137, v59
	s_waitcnt lgkmcnt(1)
	v_lshlrev_b32_e32 v60, 16, v52
	v_and_b32_e32 v61, 0xffff0000, v52
	v_lshlrev_b32_e32 v62, 16, v53
	v_and_b32_e32 v63, 0xffff0000, v53
	v_mul_f32_e32 v56, v56, v60
	v_mul_f32_e32 v57, v57, v61
	v_mul_f32_e32 v58, v58, v62
	v_mul_f32_e32 v59, v59, v63
	v_cvt_pk_bf16_f32 v52, v56, v57
	v_cvt_pk_bf16_f32 v53, v58, v59
	ds_write_b64 v1, v[52:53] offset:128
	ds_read_b64 v[52:53], v1 offset:160
	s_waitcnt vmcnt(6)
	v_mul_f32_e32 v56, v86, v50
	v_mul_f32_e32 v57, v87, v50
	v_mul_f32_e32 v58, v88, v50
	v_mul_f32_e32 v59, v89, v50
	v_mul_f32_e32 v56, v138, v56
	v_mul_f32_e32 v57, v139, v57
	v_mul_f32_e32 v58, v140, v58
	v_mul_f32_e32 v59, v141, v59
	s_waitcnt lgkmcnt(1)
	v_lshlrev_b32_e32 v60, 16, v54
	v_and_b32_e32 v61, 0xffff0000, v54
	v_lshlrev_b32_e32 v62, 16, v55
	v_and_b32_e32 v63, 0xffff0000, v55
	v_mul_f32_e32 v56, v56, v60
	v_mul_f32_e32 v57, v57, v61
	v_mul_f32_e32 v58, v58, v62
	v_mul_f32_e32 v59, v59, v63
	v_cvt_pk_bf16_f32 v54, v56, v57
	v_cvt_pk_bf16_f32 v55, v58, v59
	ds_write_b64 v1, v[54:55] offset:144
	ds_read_b64 v[54:55], v1 offset:176
	s_waitcnt vmcnt(5)
	v_mul_f32_e32 v56, v90, v50
	v_mul_f32_e32 v57, v91, v50
	v_mul_f32_e32 v58, v92, v50
	v_mul_f32_e32 v59, v93, v50
	v_mul_f32_e32 v56, v154, v56
	v_mul_f32_e32 v57, v155, v57
	v_mul_f32_e32 v58, v156, v58
	v_mul_f32_e32 v59, v157, v59
	s_waitcnt lgkmcnt(1)
	v_lshlrev_b32_e32 v60, 16, v52
	v_and_b32_e32 v61, 0xffff0000, v52
	v_lshlrev_b32_e32 v62, 16, v53
	v_and_b32_e32 v63, 0xffff0000, v53
	v_mul_f32_e32 v56, v56, v60
	v_mul_f32_e32 v57, v57, v61
	v_mul_f32_e32 v58, v58, v62
	v_mul_f32_e32 v59, v59, v63
	v_cvt_pk_bf16_f32 v52, v56, v57
	v_cvt_pk_bf16_f32 v53, v58, v59
	ds_write_b64 v1, v[52:53] offset:160
	ds_read_b64 v[52:53], v1 offset:192
	s_waitcnt vmcnt(4)
; __device__ __forceinline__ float bflo(unsigned u) { return __uint_as_float(u << 16); }
; __device__ __forceinline__ float bfhi(unsigned u) { return __uint_as_float(u & 0xffff0000u); }
; __device__ __forceinline__ void attn_unit(const PT& p, LAS unsigned char* lds, int tid, int lane, int wave, int b, int hd, int qb, float lam) {
;     ...
;         const float rn = rsqrtf(ss * (1.f / 128.f) + EPS) * (1.f - LAMBDA_INIT);
; #pragma unroll
;         for (int db = 0; db < 4; ++db)
; #pragma unroll
;             for (int qd = 0; qd < 4; ++qd) {
;                 const int d = db * 32 + 8 * qd + 4 * h; const unsigned off = tokq * 2048u + (unsigned)(hd * 128 + d);
;                 const u32x2 gg = *(const u32x2*)(Gb + off); const f32x4 sg = *(const f32x4*)(p.in[20] + d);
;                 u32x2 w; w.x = pk2(oT[db][4 * qd] * rn * sg.x * bflo(gg.x), oT[db][4 * qd + 1] * rn * sg.y * bfhi(gg.x));
;                 w.y = pk2(oT[db][4 * qd + 2] * rn * sg.z * bflo(gg.y), oT[db][4 * qd + 3] * rn * sg.w * bfhi(gg.y));
;                 *(u32x2*)(Ob + off) = w;
;             }
;     }
	v_mul_f32_e32 v56, v94, v50
	v_mul_f32_e32 v57, v95, v50
	v_mul_f32_e32 v58, v96, v50
	v_mul_f32_e32 v59, v97, v50
	v_mul_f32_e32 v56, v158, v56
	v_mul_f32_e32 v57, v159, v57
	v_mul_f32_e32 v58, v160, v58
	v_mul_f32_e32 v59, v161, v59
	s_waitcnt lgkmcnt(1)
	v_lshlrev_b32_e32 v60, 16, v54
	v_and_b32_e32 v61, 0xffff0000, v54
	v_lshlrev_b32_e32 v62, 16, v55
	v_and_b32_e32 v63, 0xffff0000, v55
	v_mul_f32_e32 v56, v56, v60
	v_mul_f32_e32 v57, v57, v61
	v_mul_f32_e32 v58, v58, v62
	v_mul_f32_e32 v59, v59, v63
	v_cvt_pk_bf16_f32 v54, v56, v57
	v_cvt_pk_bf16_f32 v55, v58, v59
	ds_write_b64 v1, v[54:55] offset:176
	ds_read_b64 v[54:55], v1 offset:208
	s_waitcnt vmcnt(3)
	v_mul_f32_e32 v56, v66, v50
	v_mul_f32_e32 v57, v67, v50
	v_mul_f32_e32 v58, v68, v50
	v_mul_f32_e32 v59, v69, v50
	v_mul_f32_e32 v56, v162, v56
	v_mul_f32_e32 v57, v163, v57
	v_mul_f32_e32 v58, v164, v58
	v_mul_f32_e32 v59, v165, v59
	s_waitcnt lgkmcnt(1)
	v_lshlrev_b32_e32 v60, 16, v52
	v_and_b32_e32 v61, 0xffff0000, v52
	v_lshlrev_b32_e32 v62, 16, v53
	v_and_b32_e32 v63, 0xffff0000, v53
	v_mul_f32_e32 v56, v56, v60
	v_mul_f32_e32 v57, v57, v61
	v_mul_f32_e32 v58, v58, v62
	v_mul_f32_e32 v59, v59, v63
	v_cvt_pk_bf16_f32 v52, v56, v57
	v_cvt_pk_bf16_f32 v53, v58, v59
	ds_write_b64 v1, v[52:53] offset:192
	ds_read_b64 v[52:53], v1 offset:224
	s_waitcnt vmcnt(2)
	v_mul_f32_e32 v56, v70, v50
	v_mul_f32_e32 v57, v71, v50
	v_mul_f32_e32 v58, v72, v50
	v_mul_f32_e32 v59, v73, v50
	v_mul_f32_e32 v56, v166, v56
	v_mul_f32_e32 v57, v167, v57
	v_mul_f32_e32 v58, v168, v58
	v_mul_f32_e32 v59, v169, v59
	s_waitcnt lgkmcnt(1)
	v_lshlrev_b32_e32 v60, 16, v54
	v_and_b32_e32 v61, 0xffff0000, v54
	v_lshlrev_b32_e32 v62, 16, v55
	v_and_b32_e32 v63, 0xffff0000, v55
	v_mul_f32_e32 v56, v56, v60
	v_mul_f32_e32 v57, v57, v61
	v_mul_f32_e32 v58, v58, v62
	v_mul_f32_e32 v59, v59, v63
	v_cvt_pk_bf16_f32 v54, v56, v57
	v_cvt_pk_bf16_f32 v55, v58, v59
	ds_write_b64 v1, v[54:55] offset:208
	ds_read_b64 v[54:55], v1 offset:240
	s_waitcnt vmcnt(1)
	v_mul_f32_e32 v56, v74, v50
	v_mul_f32_e32 v57, v75, v50
	v_mul_f32_e32 v58, v76, v50
	v_mul_f32_e32 v59, v77, v50
	v_mul_f32_e32 v56, v170, v56
	v_mul_f32_e32 v57, v171, v57
	v_mul_f32_e32 v58, v172, v58
	v_mul_f32_e32 v59, v173, v59
	s_waitcnt lgkmcnt(1)
	v_lshlrev_b32_e32 v60, 16, v52
	v_and_b32_e32 v61, 0xffff0000, v52
	v_lshlrev_b32_e32 v62, 16, v53
	v_and_b32_e32 v63, 0xffff0000, v53
	v_mul_f32_e32 v56, v56, v60
	v_mul_f32_e32 v57, v57, v61
	v_mul_f32_e32 v58, v58, v62
	v_mul_f32_e32 v59, v59, v63
	v_cvt_pk_bf16_f32 v52, v56, v57
	v_cvt_pk_bf16_f32 v53, v58, v59
	ds_write_b64 v1, v[52:53] offset:224
	s_waitcnt vmcnt(0)
	v_mul_f32_e32 v56, v78, v50
	v_mul_f32_e32 v57, v79, v50
	v_mul_f32_e32 v58, v80, v50
	v_mul_f32_e32 v59, v81, v50
	v_mul_f32_e32 v56, v174, v56
	v_mul_f32_e32 v57, v175, v57
	v_mul_f32_e32 v58, v176, v58
	v_mul_f32_e32 v59, v177, v59
	s_waitcnt lgkmcnt(0)
	v_lshlrev_b32_e32 v60, 16, v54
	v_and_b32_e32 v61, 0xffff0000, v54
	v_lshlrev_b32_e32 v62, 16, v55
	v_and_b32_e32 v63, 0xffff0000, v55
	v_mul_f32_e32 v56, v56, v60
	v_mul_f32_e32 v57, v57, v61
	v_mul_f32_e32 v58, v58, v62
	v_mul_f32_e32 v59, v59, v63
	v_cvt_pk_bf16_f32 v54, v56, v57
	v_cvt_pk_bf16_f32 v55, v58, v59
	ds_write_b64 v1, v[54:55] offset:240
	s_waitcnt lgkmcnt(0)
	ds_read_b128 v[18:21], v15
	ds_read_b128 v[22:25], v15 offset:1088
	ds_read_b128 v[26:29], v15 offset:2176
	ds_read_b128 v[30:33], v15 offset:3264
	ds_read_b128 v[34:37], v15 offset:4352
	ds_read_b128 v[38:41], v15 offset:5440
	ds_read_b128 v[42:45], v15 offset:6528
	ds_read_b128 v[46:49], v15 offset:7616
	s_mov_b64 s[98:99], s[44:45]
	s_waitcnt lgkmcnt(7)
	global_store_dwordx4 v14, v[18:21], s[98:99]
	s_add_u32 s98, s98, 0x4000
	s_addc_u32 s99, s99, 0
	s_waitcnt lgkmcnt(6)
	global_store_dwordx4 v14, v[22:25], s[98:99]
	s_add_u32 s98, s98, 0x4000
	s_addc_u32 s99, s99, 0
	s_waitcnt lgkmcnt(5)
	global_store_dwordx4 v14, v[26:29], s[98:99]
	s_add_u32 s98, s98, 0x4000
	s_addc_u32 s99, s99, 0
	s_waitcnt lgkmcnt(4)
	global_store_dwordx4 v14, v[30:33], s[98:99]
	s_add_u32 s98, s98, 0x4000
	s_addc_u32 s99, s99, 0
	s_waitcnt lgkmcnt(3)
	global_store_dwordx4 v14, v[34:37], s[98:99]
	s_add_u32 s98, s98, 0x4000
	s_addc_u32 s99, s99, 0
	s_waitcnt lgkmcnt(2)
	global_store_dwordx4 v14, v[38:41], s[98:99]
	s_add_u32 s98, s98, 0x4000
	s_addc_u32 s99, s99, 0
	s_waitcnt lgkmcnt(1)
	global_store_dwordx4 v14, v[42:45], s[98:99]
	s_add_u32 s98, s98, 0x4000
	s_addc_u32 s99, s99, 0
	s_waitcnt lgkmcnt(0)
	global_store_dwordx4 v14, v[46:49], s[98:99]
	s_branch .LBB0_1073
